# virtual workgroup ids built from (XCC id, arrival rank within the XCC) so that the tile-ownership groups always coincide with physical XCDs: local barriers and L2 tile sharing no longer depend on disp
# speedup vs baseline: 1.0137x; 1.0137x over previous
_Z8mega_fwd6Params:
	s_mov_b64 s[82:83], s[0:1]
	s_load_dwordx2 s[0:1], s[0:1], 0x100
	s_nop 0
	s_load_dwordx4 s[40:43], s[82:83], 0x210
	s_load_dwordx2 s[26:27], s[82:83], 0x220
	s_add_u32 s4, s82, 0x220
	s_addc_u32 s5, s83, 0
	v_and_b32_e32 v1, 0x3ff, v0
	v_writelane_b32 v252, s4, 0
	v_cmp_gt_u32_e32 vcc, 3, v1
	s_nop 0
	v_writelane_b32 v252, s5, 1
	s_and_saveexec_b64 s[4:5], vcc
	v_lshl_add_u32 v2, v1, 2, 0
	v_add_u32_e32 v2, 0x23800, v2
	v_mov_b32_e32 v3, 0
	ds_write_b32 v2, v3
	s_or_b64 exec, exec, s[4:5]
	s_waitcnt lgkmcnt(0)
	s_barrier
	s_add_u32 s4, s0, 0x300000
	s_getreg_b32 s3, hwreg(HW_REG_XCC_ID, 0, 4)
	s_addc_u32 s5, s1, 0
	s_and_b32 s3, s3, 15
	v_cmp_eq_u32_e32 vcc, 0, v1
	s_and_saveexec_b64 s[6:7], vcc
	s_cbranch_execz .LBB0_5
	s_mov_b64 s[8:9], exec
	v_mbcnt_lo_u32_b32 v2, s8, 0
	v_mbcnt_hi_u32_b32 v2, s9, v2
	v_cmp_eq_u32_e32 vcc, 0, v2
	s_and_b64 s[10:11], exec, vcc
	s_mov_b64 exec, s[10:11]
	s_cbranch_execz .LBB0_5
	s_lshl_b32 s10, s3, 8
	s_bcnt1_i32_b64 s8, s[8:9]
	v_mov_b32_e32 v2, s10
	v_mov_b32_e32 v3, s8
	global_atomic_add v4, v2, v3, s[4:5] offset:1024 sc0
	s_waitcnt vmcnt(0)
	v_mov_b32_e32 v5, 0x2380c
	ds_write_b32 v5, v4
	s_waitcnt lgkmcnt(0)
.LBB0_5:
	s_or_b64 exec, exec, s[6:7]
	s_barrier
	v_mov_b32_e32 v5, 0x2380c
	ds_read_b32 v4, v5
	s_waitcnt lgkmcnt(0)
	v_readfirstlane_b32 s8, v4
	s_cmpk_lg_i32 s26, 0x100
	s_cbranch_scc1 .Lkeep_bx
	s_cmp_gt_u32 s8, 31
	s_cbranch_scc1 .Lkeep_bx
	s_cmp_gt_u32 s3, 7
	s_cbranch_scc1 .Lkeep_bx
	s_lshl_b32 s2, s8, 3
	s_or_b32 s2, s2, s3
.Lkeep_bx:
	v_cmp_eq_u32_e32 vcc, 0, v1
	s_and_saveexec_b64 s[6:7], vcc
	s_cbranch_execz .Lmask_done
	s_and_b32 s10, s2, 7
	s_lshl_b32 s10, s10, 2
	s_addk_i32 s10, 0x3800
	s_lshl_b32 s8, 1, s3
	v_mov_b32_e32 v2, s10
	v_mov_b32_e32 v3, s8
	global_atomic_or v2, v3, s[4:5]
